# EpiMlpIn hand-written v2 with permlane-swap row reductions and nt stores; on v099
# baseline (speedup 1.0000x reference)
; __device__ __forceinline__ u32x4 pack8(const f32x4 v0, const f32x4 v1) { u32x4 w; w.x = cvt_pk_bf16(v0[0], v0[1]); w.y = cvt_pk_bf16(v0[2], v0[3]); w.z = cvt_pk_bf16(v1[0], v1[1]); w.w = cvt_pk_bf16(v1[2], v1[3]); return w; }
; __device__ __forceinline__ void row_rs8(float (&rs)[8], const float* ssq, int row0, int fq) {
;     ...
;     for (int i = 0; i < 8; ++i) p[i] = *(const f32x4*)(ssq + (size_t)(row0 + (i >> 2) * HALF + (i & 3) * 16) * 16 + 4 * fq);
; #pragma unroll
;     for (int i = 0; i < 8; ++i) { float s = (p[i][0] + p[i][1]) + (p[i][2] + p[i][3]); s += __shfl_xor(s, 16); s += __shfl_xor(s, 32); rs[i] = __builtin_amdgcn_rsqf(s * (1.0f / DMODEL) + RMS_EPS); }
;     __device__ __forceinline__ void operator()(const f32x4 (&acc)[2][2][4][2], const Unit& u, int wr, int wc, int fr, int fq) const {
;     ...
;         float rs[8]; row_rs8(rs, ssq, row0, fq);
; #pragma unroll
;         for (int ai = 0; ai < 2; ++ai)
; #pragma unroll
;             for (int m = 0; m < 4; ++m) { const int row = row0 + ai * HALF + m * 16; const float r = rs[ai * 4 + m];
;                 bf16_t* rowp = O + (size_t)row * ldc + col0;
; #pragma unroll
;                 for (int bj = 0; bj < 2; ++bj) { f32x4 v0 = acc[ai][bj][m][0] * r, v1 = acc[ai][bj][m][1] * r;
; #pragma unroll
;                     for (int e = 0; e < 4; ++e) { const float a = fmaxf(v0[e], 0.f), b = fmaxf(v1[e], 0.f); v0[e] = a * a; v1[e] = b * b; }
;                     *(u32x4*)(rowp + bj * HALF) = pack8(v0, v1); } }
.LBB0_614:
	v_readfirstlane_b32 s11, v192
	v_and_b32_e32 v176, 15, v192
	s_lshl_b32 s13, s22, 8
	s_lshr_b32 s22, s11, 8
	s_lshl_b32 s22, s22, 6
	s_add_i32 s22, s22, s13
	v_add_u32_e32 v176, s22, v176
	v_bfe_u32 v177, v192, 4, 2
	s_lshr_b32 s11, s11, 1
	s_and_b32 s11, s11, 0x60
	s_lshl_b32 s13, s20, 8
	s_or_b32 s11, s11, s13
	v_lshl_or_b32 v178, v177, 3, s11
	v_lshlrev_b32_e32 v172, 13, v176
	v_lshl_add_u32 v172, v178, 1, v172
	v_lshlrev_b32_e32 v173, 6, v176
	v_lshl_add_u32 v173, v177, 4, v173
	global_load_dwordx4 v[128:131], v173, s[6:7]
	v_add_u32_e32 v178, 0x400, v173
	global_load_dwordx4 v[132:135], v178, s[6:7]
	v_add_u32_e32 v178, 0x800, v173
	global_load_dwordx4 v[136:139], v178, s[6:7]
	v_add_u32_e32 v178, 0xc00, v173
	global_load_dwordx4 v[140:143], v178, s[6:7]
	v_add_u32_e32 v178, 0x2000, v173
	global_load_dwordx4 v[144:147], v178, s[6:7]
	v_add_u32_e32 v178, 0x2400, v173
	global_load_dwordx4 v[148:151], v178, s[6:7]
	v_add_u32_e32 v178, 0x2800, v173
	global_load_dwordx4 v[164:167], v178, s[6:7]
	v_add_u32_e32 v178, 0x2c00, v173
	global_load_dwordx4 v[168:171], v178, s[6:7]
	v_xor_b32_e32 v174, 16, v241
	v_xor_b32_e32 v175, 32, v241
	v_lshlrev_b32_e32 v174, 2, v174
	v_lshlrev_b32_e32 v175, 2, v175
	s_waitcnt vmcnt(7)
	v_add_f32_e32 v176, v128, v129
	v_add_f32_e32 v177, v130, v131
	v_add_f32_e32 v176, v176, v177
	v_mov_b32_e32 v177, v176
	s_nop 1
	v_permlane16_swap_b32_e32 v176, v177
	v_add_f32_e32 v176, v176, v177
	v_mov_b32_e32 v177, v176
	v_mov_b32_e32 v178, v172
	s_nop 0
	v_permlane32_swap_b32_e32 v176, v177
	v_add_f32_e32 v176, v176, v177
	v_fmamk_f32 v176, v176, 0x3a800000, v193
	v_rsq_f32_e32 v180, v176
	s_nop 0
	v_pk_mul_f32 v[124:125], v[124:125], v[180:181] op_sel_hi:[1,0]
	v_pk_mul_f32 v[126:127], v[126:127], v[180:181] op_sel_hi:[1,0]
	v_pk_mul_f32 v[120:121], v[120:121], v[180:181] op_sel_hi:[1,0]
	v_pk_mul_f32 v[122:123], v[122:123], v[180:181] op_sel_hi:[1,0]
	v_max_f32_e32 v124, 0, v124
	v_max_f32_e32 v125, 0, v125
	v_max_f32_e32 v126, 0, v126
	v_max_f32_e32 v127, 0, v127
	v_max_f32_e32 v120, 0, v120
	v_max_f32_e32 v121, 0, v121
	v_max_f32_e32 v122, 0, v122
	v_max_f32_e32 v123, 0, v123
	v_pk_mul_f32 v[124:125], v[124:125], v[124:125]
	v_pk_mul_f32 v[126:127], v[126:127], v[126:127]
	v_pk_mul_f32 v[120:121], v[120:121], v[120:121]
	v_pk_mul_f32 v[122:123], v[122:123], v[122:123]
	v_cvt_pk_bf16_f32 v124, v124, v125
	v_cvt_pk_bf16_f32 v125, v126, v127
	v_cvt_pk_bf16_f32 v126, v120, v121
	v_cvt_pk_bf16_f32 v127, v122, v123
	global_store_dwordx4 v178, v[124:127], s[0:1] nt
	v_pk_mul_f32 v[116:117], v[116:117], v[180:181] op_sel_hi:[1,0]
	v_pk_mul_f32 v[118:119], v[118:119], v[180:181] op_sel_hi:[1,0]
	v_pk_mul_f32 v[112:113], v[112:113], v[180:181] op_sel_hi:[1,0]
	v_pk_mul_f32 v[114:115], v[114:115], v[180:181] op_sel_hi:[1,0]
	v_max_f32_e32 v116, 0, v116
	v_max_f32_e32 v117, 0, v117
	v_max_f32_e32 v118, 0, v118
	v_max_f32_e32 v119, 0, v119
	v_max_f32_e32 v112, 0, v112
	v_max_f32_e32 v113, 0, v113
	v_max_f32_e32 v114, 0, v114
	v_max_f32_e32 v115, 0, v115
	v_pk_mul_f32 v[116:117], v[116:117], v[116:117]
	v_pk_mul_f32 v[118:119], v[118:119], v[118:119]
	v_pk_mul_f32 v[112:113], v[112:113], v[112:113]
	v_pk_mul_f32 v[114:115], v[114:115], v[114:115]
	v_cvt_pk_bf16_f32 v116, v116, v117
	v_cvt_pk_bf16_f32 v117, v118, v119
	v_cvt_pk_bf16_f32 v118, v112, v113
	v_cvt_pk_bf16_f32 v119, v114, v115
	global_store_dwordx4 v178, v[116:119], s[0:1] offset:256 nt
	s_waitcnt vmcnt(8)
	v_add_f32_e32 v176, v132, v133
	v_add_f32_e32 v177, v134, v135
	v_add_f32_e32 v176, v176, v177
	v_mov_b32_e32 v177, v176
	s_nop 1
	v_permlane16_swap_b32_e32 v176, v177
	v_add_f32_e32 v176, v176, v177
	v_mov_b32_e32 v177, v176
	v_add_u32_e32 v178, 0x20000, v172
	s_nop 0
	v_permlane32_swap_b32_e32 v176, v177
	v_add_f32_e32 v176, v176, v177
	v_fmamk_f32 v176, v176, 0x3a800000, v193
	v_rsq_f32_e32 v180, v176
	s_nop 0
	v_pk_mul_f32 v[108:109], v[108:109], v[180:181] op_sel_hi:[1,0]
	v_pk_mul_f32 v[110:111], v[110:111], v[180:181] op_sel_hi:[1,0]
	v_pk_mul_f32 v[104:105], v[104:105], v[180:181] op_sel_hi:[1,0]
	v_pk_mul_f32 v[106:107], v[106:107], v[180:181] op_sel_hi:[1,0]
	v_max_f32_e32 v108, 0, v108
	v_max_f32_e32 v109, 0, v109
	v_max_f32_e32 v110, 0, v110
	v_max_f32_e32 v111, 0, v111
	v_max_f32_e32 v104, 0, v104
	v_max_f32_e32 v105, 0, v105
	v_max_f32_e32 v106, 0, v106
	v_max_f32_e32 v107, 0, v107
	v_pk_mul_f32 v[108:109], v[108:109], v[108:109]
	v_pk_mul_f32 v[110:111], v[110:111], v[110:111]
	v_pk_mul_f32 v[104:105], v[104:105], v[104:105]
	v_pk_mul_f32 v[106:107], v[106:107], v[106:107]
	v_cvt_pk_bf16_f32 v108, v108, v109
	v_cvt_pk_bf16_f32 v109, v110, v111
	v_cvt_pk_bf16_f32 v110, v104, v105
	v_cvt_pk_bf16_f32 v111, v106, v107
	global_store_dwordx4 v178, v[108:111], s[0:1] nt
	v_pk_mul_f32 v[100:101], v[100:101], v[180:181] op_sel_hi:[1,0]
	v_pk_mul_f32 v[102:103], v[102:103], v[180:181] op_sel_hi:[1,0]
	v_pk_mul_f32 v[96:97], v[96:97], v[180:181] op_sel_hi:[1,0]
	v_pk_mul_f32 v[98:99], v[98:99], v[180:181] op_sel_hi:[1,0]
	v_max_f32_e32 v100, 0, v100
	v_max_f32_e32 v101, 0, v101
	v_max_f32_e32 v102, 0, v102
	v_max_f32_e32 v103, 0, v103
	v_max_f32_e32 v96, 0, v96
	v_max_f32_e32 v97, 0, v97
	v_max_f32_e32 v98, 0, v98
	v_max_f32_e32 v99, 0, v99
	v_pk_mul_f32 v[100:101], v[100:101], v[100:101]
	v_pk_mul_f32 v[102:103], v[102:103], v[102:103]
	v_pk_mul_f32 v[96:97], v[96:97], v[96:97]
	v_pk_mul_f32 v[98:99], v[98:99], v[98:99]
	v_cvt_pk_bf16_f32 v100, v100, v101
	v_cvt_pk_bf16_f32 v101, v102, v103
	v_cvt_pk_bf16_f32 v102, v96, v97
	v_cvt_pk_bf16_f32 v103, v98, v99
	global_store_dwordx4 v178, v[100:103], s[0:1] offset:256 nt
	s_waitcnt vmcnt(9)
; __device__ __forceinline__ u32x4 pack8(const f32x4 v0, const f32x4 v1) { u32x4 w; w.x = cvt_pk_bf16(v0[0], v0[1]); w.y = cvt_pk_bf16(v0[2], v0[3]); w.z = cvt_pk_bf16(v1[0], v1[1]); w.w = cvt_pk_bf16(v1[2], v1[3]); return w; }
; __device__ __forceinline__ void row_rs8(float (&rs)[8], const float* ssq, int row0, int fq) {
;     ...
;     for (int i = 0; i < 8; ++i) { float s = (p[i][0] + p[i][1]) + (p[i][2] + p[i][3]); s += __shfl_xor(s, 16); s += __shfl_xor(s, 32); rs[i] = __builtin_amdgcn_rsqf(s * (1.0f / DMODEL) + RMS_EPS); }
;     __device__ __forceinline__ void operator()(const f32x4 (&acc)[2][2][4][2], const Unit& u, int wr, int wc, int fr, int fq) const {
;     ...
;             for (int m = 0; m < 4; ++m) { const int row = row0 + ai * HALF + m * 16; const float r = rs[ai * 4 + m];
;                 bf16_t* rowp = O + (size_t)row * ldc + col0;
; #pragma unroll
;                 for (int bj = 0; bj < 2; ++bj) { f32x4 v0 = acc[ai][bj][m][0] * r, v1 = acc[ai][bj][m][1] * r;
; #pragma unroll
;                     for (int e = 0; e < 4; ++e) { const float a = fmaxf(v0[e], 0.f), b = fmaxf(v1[e], 0.f); v0[e] = a * a; v1[e] = b * b; }
;                     *(u32x4*)(rowp + bj * HALF) = pack8(v0, v1); } }
	v_add_f32_e32 v176, v136, v137
	v_add_f32_e32 v177, v138, v139
	v_add_f32_e32 v176, v176, v177
	v_mov_b32_e32 v177, v176
	s_nop 1
	v_permlane16_swap_b32_e32 v176, v177
	v_add_f32_e32 v176, v176, v177
	v_mov_b32_e32 v177, v176
	v_add_u32_e32 v178, 0x40000, v172
	s_nop 0
	v_permlane32_swap_b32_e32 v176, v177
	v_add_f32_e32 v176, v176, v177
	v_fmamk_f32 v176, v176, 0x3a800000, v193
	v_rsq_f32_e32 v180, v176
	s_nop 0
	v_pk_mul_f32 v[92:93], v[92:93], v[180:181] op_sel_hi:[1,0]
	v_pk_mul_f32 v[94:95], v[94:95], v[180:181] op_sel_hi:[1,0]
	v_pk_mul_f32 v[88:89], v[88:89], v[180:181] op_sel_hi:[1,0]
	v_pk_mul_f32 v[90:91], v[90:91], v[180:181] op_sel_hi:[1,0]
	v_max_f32_e32 v92, 0, v92
	v_max_f32_e32 v93, 0, v93
	v_max_f32_e32 v94, 0, v94
	v_max_f32_e32 v95, 0, v95
	v_max_f32_e32 v88, 0, v88
	v_max_f32_e32 v89, 0, v89
	v_max_f32_e32 v90, 0, v90
	v_max_f32_e32 v91, 0, v91
	v_pk_mul_f32 v[92:93], v[92:93], v[92:93]
	v_pk_mul_f32 v[94:95], v[94:95], v[94:95]
	v_pk_mul_f32 v[88:89], v[88:89], v[88:89]
	v_pk_mul_f32 v[90:91], v[90:91], v[90:91]
	v_cvt_pk_bf16_f32 v92, v92, v93
	v_cvt_pk_bf16_f32 v93, v94, v95
	v_cvt_pk_bf16_f32 v94, v88, v89
	v_cvt_pk_bf16_f32 v95, v90, v91
	global_store_dwordx4 v178, v[92:95], s[0:1] nt
	v_pk_mul_f32 v[84:85], v[84:85], v[180:181] op_sel_hi:[1,0]
	v_pk_mul_f32 v[86:87], v[86:87], v[180:181] op_sel_hi:[1,0]
	v_pk_mul_f32 v[80:81], v[80:81], v[180:181] op_sel_hi:[1,0]
	v_pk_mul_f32 v[82:83], v[82:83], v[180:181] op_sel_hi:[1,0]
	v_max_f32_e32 v84, 0, v84
	v_max_f32_e32 v85, 0, v85
	v_max_f32_e32 v86, 0, v86
	v_max_f32_e32 v87, 0, v87
	v_max_f32_e32 v80, 0, v80
	v_max_f32_e32 v81, 0, v81
	v_max_f32_e32 v82, 0, v82
	v_max_f32_e32 v83, 0, v83
	v_pk_mul_f32 v[84:85], v[84:85], v[84:85]
	v_pk_mul_f32 v[86:87], v[86:87], v[86:87]
	v_pk_mul_f32 v[80:81], v[80:81], v[80:81]
	v_pk_mul_f32 v[82:83], v[82:83], v[82:83]
	v_cvt_pk_bf16_f32 v84, v84, v85
	v_cvt_pk_bf16_f32 v85, v86, v87
	v_cvt_pk_bf16_f32 v86, v80, v81
	v_cvt_pk_bf16_f32 v87, v82, v83
	global_store_dwordx4 v178, v[84:87], s[0:1] offset:256 nt
	s_waitcnt vmcnt(10)
	v_add_f32_e32 v176, v140, v141
	v_add_f32_e32 v177, v142, v143
	v_add_f32_e32 v176, v176, v177
	v_mov_b32_e32 v177, v176
	s_nop 1
	v_permlane16_swap_b32_e32 v176, v177
	v_add_f32_e32 v176, v176, v177
	v_mov_b32_e32 v177, v176
	v_add_u32_e32 v178, 0x60000, v172
	s_nop 0
	v_permlane32_swap_b32_e32 v176, v177
	v_add_f32_e32 v176, v176, v177
	v_fmamk_f32 v176, v176, 0x3a800000, v193
	v_rsq_f32_e32 v180, v176
	s_nop 0
	v_pk_mul_f32 v[76:77], v[76:77], v[180:181] op_sel_hi:[1,0]
	v_pk_mul_f32 v[78:79], v[78:79], v[180:181] op_sel_hi:[1,0]
	v_pk_mul_f32 v[72:73], v[72:73], v[180:181] op_sel_hi:[1,0]
	v_pk_mul_f32 v[74:75], v[74:75], v[180:181] op_sel_hi:[1,0]
	v_max_f32_e32 v76, 0, v76
	v_max_f32_e32 v77, 0, v77
	v_max_f32_e32 v78, 0, v78
	v_max_f32_e32 v79, 0, v79
	v_max_f32_e32 v72, 0, v72
	v_max_f32_e32 v73, 0, v73
	v_max_f32_e32 v74, 0, v74
	v_max_f32_e32 v75, 0, v75
	v_pk_mul_f32 v[76:77], v[76:77], v[76:77]
	v_pk_mul_f32 v[78:79], v[78:79], v[78:79]
	v_pk_mul_f32 v[72:73], v[72:73], v[72:73]
	v_pk_mul_f32 v[74:75], v[74:75], v[74:75]
	v_cvt_pk_bf16_f32 v76, v76, v77
	v_cvt_pk_bf16_f32 v77, v78, v79
	v_cvt_pk_bf16_f32 v78, v72, v73
	v_cvt_pk_bf16_f32 v79, v74, v75
	global_store_dwordx4 v178, v[76:79], s[0:1] nt
	v_pk_mul_f32 v[68:69], v[68:69], v[180:181] op_sel_hi:[1,0]
	v_pk_mul_f32 v[70:71], v[70:71], v[180:181] op_sel_hi:[1,0]
	v_pk_mul_f32 v[64:65], v[64:65], v[180:181] op_sel_hi:[1,0]
	v_pk_mul_f32 v[66:67], v[66:67], v[180:181] op_sel_hi:[1,0]
	v_max_f32_e32 v68, 0, v68
	v_max_f32_e32 v69, 0, v69
	v_max_f32_e32 v70, 0, v70
	v_max_f32_e32 v71, 0, v71
	v_max_f32_e32 v64, 0, v64
	v_max_f32_e32 v65, 0, v65
	v_max_f32_e32 v66, 0, v66
	v_max_f32_e32 v67, 0, v67
	v_pk_mul_f32 v[68:69], v[68:69], v[68:69]
	v_pk_mul_f32 v[70:71], v[70:71], v[70:71]
	v_pk_mul_f32 v[64:65], v[64:65], v[64:65]
	v_pk_mul_f32 v[66:67], v[66:67], v[66:67]
	v_cvt_pk_bf16_f32 v68, v68, v69
	v_cvt_pk_bf16_f32 v69, v70, v71
	v_cvt_pk_bf16_f32 v70, v64, v65
	v_cvt_pk_bf16_f32 v71, v66, v67
	global_store_dwordx4 v178, v[68:71], s[0:1] offset:256 nt
	s_waitcnt vmcnt(11)
	v_add_f32_e32 v176, v144, v145
	v_add_f32_e32 v177, v146, v147
	v_add_f32_e32 v176, v176, v177
	v_mov_b32_e32 v177, v176
	s_nop 1
	v_permlane16_swap_b32_e32 v176, v177
	v_add_f32_e32 v176, v176, v177
	v_mov_b32_e32 v177, v176
	v_add_u32_e32 v178, 0x100000, v172
	s_nop 0
	v_permlane32_swap_b32_e32 v176, v177
	v_add_f32_e32 v176, v176, v177
	v_fmamk_f32 v176, v176, 0x3a800000, v193
	v_rsq_f32_e32 v180, v176
	s_nop 0
	v_pk_mul_f32 v[60:61], v[60:61], v[180:181] op_sel_hi:[1,0]
	v_pk_mul_f32 v[62:63], v[62:63], v[180:181] op_sel_hi:[1,0]
	v_pk_mul_f32 v[56:57], v[56:57], v[180:181] op_sel_hi:[1,0]
	v_pk_mul_f32 v[58:59], v[58:59], v[180:181] op_sel_hi:[1,0]
	v_max_f32_e32 v60, 0, v60
	v_max_f32_e32 v61, 0, v61
	v_max_f32_e32 v62, 0, v62
	v_max_f32_e32 v63, 0, v63
	v_max_f32_e32 v56, 0, v56
	v_max_f32_e32 v57, 0, v57
	v_max_f32_e32 v58, 0, v58
	v_max_f32_e32 v59, 0, v59
	v_pk_mul_f32 v[60:61], v[60:61], v[60:61]
	v_pk_mul_f32 v[62:63], v[62:63], v[62:63]
	v_pk_mul_f32 v[56:57], v[56:57], v[56:57]
	v_pk_mul_f32 v[58:59], v[58:59], v[58:59]
	v_cvt_pk_bf16_f32 v60, v60, v61
	v_cvt_pk_bf16_f32 v61, v62, v63
	v_cvt_pk_bf16_f32 v62, v56, v57
	v_cvt_pk_bf16_f32 v63, v58, v59
	global_store_dwordx4 v178, v[60:63], s[0:1] nt
	v_pk_mul_f32 v[52:53], v[52:53], v[180:181] op_sel_hi:[1,0]
	v_pk_mul_f32 v[54:55], v[54:55], v[180:181] op_sel_hi:[1,0]
	v_pk_mul_f32 v[48:49], v[48:49], v[180:181] op_sel_hi:[1,0]
	v_pk_mul_f32 v[50:51], v[50:51], v[180:181] op_sel_hi:[1,0]
	v_max_f32_e32 v52, 0, v52
	v_max_f32_e32 v53, 0, v53
	v_max_f32_e32 v54, 0, v54
	v_max_f32_e32 v55, 0, v55
	v_max_f32_e32 v48, 0, v48
	v_max_f32_e32 v49, 0, v49
	v_max_f32_e32 v50, 0, v50
	v_max_f32_e32 v51, 0, v51
	v_pk_mul_f32 v[52:53], v[52:53], v[52:53]
	v_pk_mul_f32 v[54:55], v[54:55], v[54:55]
	v_pk_mul_f32 v[48:49], v[48:49], v[48:49]
	v_pk_mul_f32 v[50:51], v[50:51], v[50:51]
	v_cvt_pk_bf16_f32 v52, v52, v53
	v_cvt_pk_bf16_f32 v53, v54, v55
	v_cvt_pk_bf16_f32 v54, v48, v49
	v_cvt_pk_bf16_f32 v55, v50, v51
	global_store_dwordx4 v178, v[52:55], s[0:1] offset:256 nt
	s_waitcnt vmcnt(12)
; __device__ __forceinline__ u32x4 pack8(const f32x4 v0, const f32x4 v1) { u32x4 w; w.x = cvt_pk_bf16(v0[0], v0[1]); w.y = cvt_pk_bf16(v0[2], v0[3]); w.z = cvt_pk_bf16(v1[0], v1[1]); w.w = cvt_pk_bf16(v1[2], v1[3]); return w; }
; __device__ __forceinline__ void row_rs8(float (&rs)[8], const float* ssq, int row0, int fq) {
;     ...
;     for (int i = 0; i < 8; ++i) { float s = (p[i][0] + p[i][1]) + (p[i][2] + p[i][3]); s += __shfl_xor(s, 16); s += __shfl_xor(s, 32); rs[i] = __builtin_amdgcn_rsqf(s * (1.0f / DMODEL) + RMS_EPS); }
;     __device__ __forceinline__ void operator()(const f32x4 (&acc)[2][2][4][2], const Unit& u, int wr, int wc, int fr, int fq) const {
;     ...
;             for (int m = 0; m < 4; ++m) { const int row = row0 + ai * HALF + m * 16; const float r = rs[ai * 4 + m];
;                 bf16_t* rowp = O + (size_t)row * ldc + col0;
; #pragma unroll
;                 for (int bj = 0; bj < 2; ++bj) { f32x4 v0 = acc[ai][bj][m][0] * r, v1 = acc[ai][bj][m][1] * r;
; #pragma unroll
;                     for (int e = 0; e < 4; ++e) { const float a = fmaxf(v0[e], 0.f), b = fmaxf(v1[e], 0.f); v0[e] = a * a; v1[e] = b * b; }
;                     *(u32x4*)(rowp + bj * HALF) = pack8(v0, v1); } }
	v_add_f32_e32 v176, v148, v149
	v_add_f32_e32 v177, v150, v151
	v_add_f32_e32 v176, v176, v177
	v_mov_b32_e32 v177, v176
	s_nop 1
	v_permlane16_swap_b32_e32 v176, v177
	v_add_f32_e32 v176, v176, v177
	v_mov_b32_e32 v177, v176
	v_add_u32_e32 v178, 0x120000, v172
	s_nop 0
	v_permlane32_swap_b32_e32 v176, v177
	v_add_f32_e32 v176, v176, v177
	v_fmamk_f32 v176, v176, 0x3a800000, v193
	v_rsq_f32_e32 v180, v176
	s_nop 0
	v_pk_mul_f32 v[44:45], v[44:45], v[180:181] op_sel_hi:[1,0]
	v_pk_mul_f32 v[46:47], v[46:47], v[180:181] op_sel_hi:[1,0]
	v_pk_mul_f32 v[40:41], v[40:41], v[180:181] op_sel_hi:[1,0]
	v_pk_mul_f32 v[42:43], v[42:43], v[180:181] op_sel_hi:[1,0]
	v_max_f32_e32 v44, 0, v44
	v_max_f32_e32 v45, 0, v45
	v_max_f32_e32 v46, 0, v46
	v_max_f32_e32 v47, 0, v47
	v_max_f32_e32 v40, 0, v40
	v_max_f32_e32 v41, 0, v41
	v_max_f32_e32 v42, 0, v42
	v_max_f32_e32 v43, 0, v43
	v_pk_mul_f32 v[44:45], v[44:45], v[44:45]
	v_pk_mul_f32 v[46:47], v[46:47], v[46:47]
	v_pk_mul_f32 v[40:41], v[40:41], v[40:41]
	v_pk_mul_f32 v[42:43], v[42:43], v[42:43]
	v_cvt_pk_bf16_f32 v44, v44, v45
	v_cvt_pk_bf16_f32 v45, v46, v47
	v_cvt_pk_bf16_f32 v46, v40, v41
	v_cvt_pk_bf16_f32 v47, v42, v43
	global_store_dwordx4 v178, v[44:47], s[0:1] nt
	v_pk_mul_f32 v[36:37], v[36:37], v[180:181] op_sel_hi:[1,0]
	v_pk_mul_f32 v[38:39], v[38:39], v[180:181] op_sel_hi:[1,0]
	v_pk_mul_f32 v[32:33], v[32:33], v[180:181] op_sel_hi:[1,0]
	v_pk_mul_f32 v[34:35], v[34:35], v[180:181] op_sel_hi:[1,0]
	v_max_f32_e32 v36, 0, v36
	v_max_f32_e32 v37, 0, v37
	v_max_f32_e32 v38, 0, v38
	v_max_f32_e32 v39, 0, v39
	v_max_f32_e32 v32, 0, v32
	v_max_f32_e32 v33, 0, v33
	v_max_f32_e32 v34, 0, v34
	v_max_f32_e32 v35, 0, v35
	v_pk_mul_f32 v[36:37], v[36:37], v[36:37]
	v_pk_mul_f32 v[38:39], v[38:39], v[38:39]
	v_pk_mul_f32 v[32:33], v[32:33], v[32:33]
	v_pk_mul_f32 v[34:35], v[34:35], v[34:35]
	v_cvt_pk_bf16_f32 v36, v36, v37
	v_cvt_pk_bf16_f32 v37, v38, v39
	v_cvt_pk_bf16_f32 v38, v32, v33
	v_cvt_pk_bf16_f32 v39, v34, v35
	global_store_dwordx4 v178, v[36:39], s[0:1] offset:256 nt
	s_waitcnt vmcnt(13)
	v_add_f32_e32 v176, v164, v165
	v_add_f32_e32 v177, v166, v167
	v_add_f32_e32 v176, v176, v177
	v_mov_b32_e32 v177, v176
	s_nop 1
	v_permlane16_swap_b32_e32 v176, v177
	v_add_f32_e32 v176, v176, v177
	v_mov_b32_e32 v177, v176
	v_add_u32_e32 v178, 0x140000, v172
	s_nop 0
	v_permlane32_swap_b32_e32 v176, v177
	v_add_f32_e32 v176, v176, v177
	v_fmamk_f32 v176, v176, 0x3a800000, v193
	v_rsq_f32_e32 v180, v176
	s_nop 0
	v_pk_mul_f32 v[28:29], v[28:29], v[180:181] op_sel_hi:[1,0]
	v_pk_mul_f32 v[30:31], v[30:31], v[180:181] op_sel_hi:[1,0]
	v_pk_mul_f32 v[24:25], v[24:25], v[180:181] op_sel_hi:[1,0]
	v_pk_mul_f32 v[26:27], v[26:27], v[180:181] op_sel_hi:[1,0]
	v_max_f32_e32 v28, 0, v28
	v_max_f32_e32 v29, 0, v29
	v_max_f32_e32 v30, 0, v30
	v_max_f32_e32 v31, 0, v31
	v_max_f32_e32 v24, 0, v24
	v_max_f32_e32 v25, 0, v25
	v_max_f32_e32 v26, 0, v26
	v_max_f32_e32 v27, 0, v27
	v_pk_mul_f32 v[28:29], v[28:29], v[28:29]
	v_pk_mul_f32 v[30:31], v[30:31], v[30:31]
	v_pk_mul_f32 v[24:25], v[24:25], v[24:25]
	v_pk_mul_f32 v[26:27], v[26:27], v[26:27]
	v_cvt_pk_bf16_f32 v28, v28, v29
	v_cvt_pk_bf16_f32 v29, v30, v31
	v_cvt_pk_bf16_f32 v30, v24, v25
	v_cvt_pk_bf16_f32 v31, v26, v27
	global_store_dwordx4 v178, v[28:31], s[0:1] nt
	v_pk_mul_f32 v[20:21], v[20:21], v[180:181] op_sel_hi:[1,0]
	v_pk_mul_f32 v[22:23], v[22:23], v[180:181] op_sel_hi:[1,0]
	v_pk_mul_f32 v[16:17], v[16:17], v[180:181] op_sel_hi:[1,0]
	v_pk_mul_f32 v[18:19], v[18:19], v[180:181] op_sel_hi:[1,0]
	v_max_f32_e32 v20, 0, v20
	v_max_f32_e32 v21, 0, v21
	v_max_f32_e32 v22, 0, v22
	v_max_f32_e32 v23, 0, v23
	v_max_f32_e32 v16, 0, v16
	v_max_f32_e32 v17, 0, v17
	v_max_f32_e32 v18, 0, v18
	v_max_f32_e32 v19, 0, v19
	v_pk_mul_f32 v[20:21], v[20:21], v[20:21]
	v_pk_mul_f32 v[22:23], v[22:23], v[22:23]
	v_pk_mul_f32 v[16:17], v[16:17], v[16:17]
	v_pk_mul_f32 v[18:19], v[18:19], v[18:19]
	v_cvt_pk_bf16_f32 v20, v20, v21
	v_cvt_pk_bf16_f32 v21, v22, v23
	v_cvt_pk_bf16_f32 v22, v16, v17
	v_cvt_pk_bf16_f32 v23, v18, v19
	global_store_dwordx4 v178, v[20:23], s[0:1] offset:256 nt
	s_waitcnt vmcnt(14)
	v_add_f32_e32 v176, v168, v169
	v_add_f32_e32 v177, v170, v171
	v_add_f32_e32 v176, v176, v177
	v_mov_b32_e32 v177, v176
	s_nop 1
	v_permlane16_swap_b32_e32 v176, v177
	v_add_f32_e32 v176, v176, v177
	v_mov_b32_e32 v177, v176
	v_add_u32_e32 v178, 0x160000, v172
	s_nop 0
	v_permlane32_swap_b32_e32 v176, v177
	v_add_f32_e32 v176, v176, v177
	v_fmamk_f32 v176, v176, 0x3a800000, v193
	v_rsq_f32_e32 v180, v176
	s_nop 0
	v_pk_mul_f32 v[12:13], v[12:13], v[180:181] op_sel_hi:[1,0]
	v_pk_mul_f32 v[14:15], v[14:15], v[180:181] op_sel_hi:[1,0]
	v_pk_mul_f32 v[8:9], v[8:9], v[180:181] op_sel_hi:[1,0]
	v_pk_mul_f32 v[10:11], v[10:11], v[180:181] op_sel_hi:[1,0]
	v_max_f32_e32 v12, 0, v12
	v_max_f32_e32 v13, 0, v13
	v_max_f32_e32 v14, 0, v14
	v_max_f32_e32 v15, 0, v15
	v_max_f32_e32 v8, 0, v8
	v_max_f32_e32 v9, 0, v9
	v_max_f32_e32 v10, 0, v10
	v_max_f32_e32 v11, 0, v11
	v_pk_mul_f32 v[12:13], v[12:13], v[12:13]
	v_pk_mul_f32 v[14:15], v[14:15], v[14:15]
	v_pk_mul_f32 v[8:9], v[8:9], v[8:9]
	v_pk_mul_f32 v[10:11], v[10:11], v[10:11]
	v_cvt_pk_bf16_f32 v12, v12, v13
	v_cvt_pk_bf16_f32 v13, v14, v15
	v_cvt_pk_bf16_f32 v14, v8, v9
	v_cvt_pk_bf16_f32 v15, v10, v11
	global_store_dwordx4 v178, v[12:15], s[0:1] nt
	v_pk_mul_f32 v[4:5], v[4:5], v[180:181] op_sel_hi:[1,0]
	v_pk_mul_f32 v[6:7], v[6:7], v[180:181] op_sel_hi:[1,0]
	v_pk_mul_f32 v[0:1], v[0:1], v[180:181] op_sel_hi:[1,0]
	v_pk_mul_f32 v[2:3], v[2:3], v[180:181] op_sel_hi:[1,0]
	v_max_f32_e32 v4, 0, v4
	v_max_f32_e32 v5, 0, v5
	v_max_f32_e32 v6, 0, v6
	v_max_f32_e32 v7, 0, v7
	v_max_f32_e32 v0, 0, v0
	v_max_f32_e32 v1, 0, v1
	v_max_f32_e32 v2, 0, v2
	v_max_f32_e32 v3, 0, v3
	v_pk_mul_f32 v[4:5], v[4:5], v[4:5]
	v_pk_mul_f32 v[6:7], v[6:7], v[6:7]
	v_pk_mul_f32 v[0:1], v[0:1], v[0:1]
	v_pk_mul_f32 v[2:3], v[2:3], v[2:3]
	v_cvt_pk_bf16_f32 v4, v4, v5
	v_cvt_pk_bf16_f32 v5, v6, v7
	v_cvt_pk_bf16_f32 v6, v0, v1
	v_cvt_pk_bf16_f32 v7, v2, v3
	global_store_dwordx4 v178, v[4:7], s[0:1] offset:256 nt
	s_mov_b64 s[26:27], -1
	s_andn2_b64 vcc, exec, s[14:15]
	s_mov_b64 s[14:15], -1
	s_cbranch_vccnz .LBB0_601
	s_andn2_b64 vcc, exec, s[4:5]
	s_cbranch_vccnz .LBB0_600
	s_barrier
	s_branch .LBB0_600
